# layer-1/FFN weight conversion tiles rebalanced between the two scan phases (split index 3632 -> 2880) so the 16 conversion workgroups are no longer the critical path of scan pass A
# speedup vs baseline: 1.0910x; 1.0198x over previous
.LBB0_469:
	s_add_i32 s0, s33, 0xffffff10
	s_cmpk_gt_u32 s0, 0x85f
	s_cbranch_scc1 .LBB0_492
	v_lshlrev_b32_e32 v2, 2, v1
	v_lshrrev_b32_e32 v3, 3, v188
	v_add_u32_e32 v39, 0, v2
	v_readlane_b32 s8, v254, 0
	v_and_b32_e32 v26, 0x78, v3
	v_or_b32_e32 v33, 7, v3
	v_lshl_add_u32 v3, v1, 8, v39
	v_readlane_b32 s9, v254, 1
	v_readlane_b32 s10, v254, 2
	v_readlane_b32 s11, v254, 3
	v_readlane_b32 s12, v254, 4
	v_readlane_b32 s13, v254, 5
	v_lshl_add_u32 v34, v26, 2, v3
	v_lshl_add_u32 v35, v33, 2, v3
	v_mov_b32_e32 v3, 0
	v_readlane_b32 s14, v254, 6
	v_readlane_b32 s15, v254, 7
	s_mov_b64 s[6:7], s[10:11]
	s_mov_b64 s[8:9], s[12:13]
	v_lshl_add_u64 v[4:5], s[8:9], 0, v[2:3]
	v_lshl_add_u64 v[6:7], s[72:73], 0, v[2:3]
	v_lshl_add_u64 v[8:9], s[70:71], 0, v[2:3]
	v_lshl_add_u64 v[10:11], s[68:69], 0, v[2:3]
	v_lshl_add_u64 v[12:13], s[6:7], 0, v[2:3]
	v_lshl_add_u64 v[14:15], s[74:75], 0, v[2:3]
	v_lshlrev_b32_e32 v2, 1, v1
	v_lshl_add_u64 v[16:17], s[86:87], 0, v[2:3]
	s_mov_b64 s[2:3], 0x1880000
	v_lshl_add_u64 v[18:19], v[16:17], 0, s[2:3]
	s_mov_b64 s[2:3], 0x1300000
	s_add_i32 s4, s33, 0x1f0
	v_mul_u32_u24_e32 v38, 0x104, v26
	s_mov_b64 s[10:11], s[14:15]
	v_lshl_add_u64 v[20:21], v[16:17], 0, s[2:3]
	s_mov_b64 s[2:3], 0x800000
	v_mul_u32_u24_e32 v40, 0x104, v33
	v_lshl_add_u64 v[22:23], v[16:17], 0, s[2:3]
	s_mov_b64 s[2:3], 0x600000
	s_lshl_b32 s6, s50, 6
	s_mul_i32 s8, s50, 0x2e000
	v_lshrrev_b32_e32 v2, 6, v188
	s_lshl_b32 s0, s4, 2
	s_lshl_b32 s10, s50, 2
	v_add_u32_e32 v38, v39, v38
	s_mov_b32 s1, 0
	v_or_b32_e32 v27, 1, v26
	v_or_b32_e32 v28, 2, v26
	v_or_b32_e32 v29, 3, v26
	v_or_b32_e32 v30, 4, v26
	v_or_b32_e32 v31, 5, v26
	v_or_b32_e32 v32, 6, v26
	v_lshl_add_u64 v[24:25], v[16:17], 0, s[2:3]
	s_lshl_b32 s5, s4, 6
	s_addk_i32 s6, 0xc400
	v_mul_u32_u24_e32 v36, 0xb80, v33
	s_mul_i32 s7, s4, 0x2e000
	s_add_i32 s8, s8, 0xfd4e0000
	v_mul_u32_u24_e32 v37, 0x5c00, v2
	s_add_i32 s9, s0, 0x3cf80
	s_addk_i32 s10, 0xfc40
	v_add_u32_e32 v39, v39, v40
	s_movk_i32 s11, 0x7fff
	s_mov_b32 s12, 0xfff00
	s_mov_b32 s13, 0x40000
	v_add_u32_e32 v40, 0x400, v38
	s_branch .LBB0_472
.LBB0_471:
	s_add_i32 s4, s4, s95
	s_add_i32 s5, s5, s6
	s_add_i32 s7, s7, s8
	s_add_i32 s9, s9, s10
	s_cmpk_lt_i32 s4, 0xb40
	s_cbranch_scc0 .LBB0_492

.LBB0_731:
	s_add_i32 s0, s33, 0xffffff10
	s_cmpk_gt_u32 s0, 0xd1f
	s_cbranch_scc1 .LBB0_770
	v_lshlrev_b32_e32 v2, 2, v1
	v_lshrrev_b32_e32 v3, 3, v188
	v_add_u32_e32 v52, 0, v2
	v_and_b32_e32 v40, 0x78, v3
	v_or_b32_e32 v47, 7, v3
	v_lshl_add_u32 v3, v1, 8, v52
	v_readlane_b32 s12, v254, 0
	v_lshl_add_u32 v48, v40, 2, v3
	v_lshl_add_u32 v49, v47, 2, v3
	v_mov_b32_e32 v3, 0
	v_readlane_b32 s14, v254, 2
	v_readlane_b32 s15, v254, 3
	v_readlane_b32 s16, v254, 4
	v_readlane_b32 s17, v254, 5
	v_lshl_add_u64 v[4:5], s[84:85], 0, v[2:3]
	v_lshl_add_u64 v[8:9], s[72:73], 0, v[2:3]
	v_lshl_add_u64 v[6:7], s[16:17], 0, v[2:3]
	v_lshl_add_u64 v[10:11], s[70:71], 0, v[2:3]
	v_lshl_add_u64 v[12:13], s[68:69], 0, v[2:3]
	v_lshl_add_u64 v[14:15], s[14:15], 0, v[2:3]
	v_lshl_add_u64 v[16:17], s[74:75], 0, v[2:3]
	v_lshlrev_b32_e32 v2, 1, v1
	s_mov_b64 s[2:3], 0xb00000
	v_lshl_add_u64 v[18:19], s[86:87], 0, v[2:3]
	v_lshl_add_u64 v[20:21], v[8:9], 0, s[2:3]
	v_lshl_add_u64 v[24:25], v[10:11], 0, s[2:3]
	v_lshl_add_u64 v[28:29], v[12:13], 0, s[2:3]
	s_mov_b64 s[2:3], 0x1e80000
	v_lshl_add_u64 v[30:31], v[18:19], 0, s[2:3]
	s_mov_b64 s[2:3], 0x1880000
	s_mov_b64 s[6:7], 0x2b80000
	v_lshl_add_u64 v[32:33], v[18:19], 0, s[2:3]
	s_mov_b64 s[2:3], 0x1300000
	s_add_i32 s4, s33, 0xa50
	v_mul_u32_u24_e32 v51, 0x104, v40
	v_readlane_b32 s13, v254, 1
	v_lshl_add_u64 v[22:23], v[18:19], 0, s[6:7]
	s_mov_b64 s[6:7], 0x2080000
	v_lshl_add_u64 v[34:35], v[18:19], 0, s[2:3]
	s_mov_b64 s[2:3], 0x800000
	v_mul_u32_u24_e32 v53, 0x104, v47
	v_lshl_add_u64 v[26:27], v[18:19], 0, s[6:7]
	v_lshl_add_u64 v[36:37], v[18:19], 0, s[2:3]
	s_mov_b64 s[2:3], 0x600000
	s_lshl_b32 s7, s50, 6
	s_mul_i32 s9, s50, 0x2e000
	v_lshrrev_b32_e32 v2, 6, v188
	s_lshl_b32 s0, s4, 2
	s_lshl_b32 s13, s50, 2
	v_add_u32_e32 v51, v52, v51
	s_mov_b32 s1, 0
	v_or_b32_e32 v41, 1, v40
	v_or_b32_e32 v42, 2, v40
	v_or_b32_e32 v43, 3, v40
	v_or_b32_e32 v44, 4, v40
	v_or_b32_e32 v45, 5, v40
	v_or_b32_e32 v46, 6, v40
	s_add_i32 s5, s50, 0xffffff10
	v_lshl_add_u64 v[38:39], v[18:19], 0, s[2:3]
	s_lshl_b32 s6, s4, 6
	s_addk_i32 s7, 0xc400
	v_mul_u32_u24_e32 v1, 0xb80, v47
	s_mul_i32 s8, s4, 0x2e000
	s_add_i32 s9, s9, 0xfd4e0000
	v_mul_u32_u24_e32 v50, 0x5c00, v2
	s_add_i32 s12, s0, 0x3b480
	s_addk_i32 s13, 0xfc40
	v_add_u32_e32 v52, v52, v53
	s_movk_i32 s14, 0x7fff
	s_mov_b32 s15, 0xfff00
	s_mov_b32 s16, 0x40000
	v_add_u32_e32 v53, 0x400, v51
	v_readlane_b32 s18, v254, 6
	v_readlane_b32 s19, v254, 7
	s_branch .LBB0_734
